# P2 Y stores nt (streaming) on top of x loads nt
# baseline (speedup 1.0000x reference)
.LBB0_265:
	s_cmpk_gt_u32 s36, 0xff
	s_waitcnt lgkmcnt(0)
	s_barrier
	s_cbranch_scc1 .LBB0_267
	ds_read2st64_b32 v[78:79], v64 offset1:1
	ds_read2st64_b32 v[80:81], v64 offset0:2 offset1:3
	ds_read2st64_b32 v[82:83], v64 offset0:4 offset1:5
	ds_read2st64_b32 v[84:85], v64 offset0:6 offset1:7
	ds_read2st64_b32 v[86:87], v64 offset0:8 offset1:9
	ds_read2st64_b32 v[126:127], v64 offset0:10 offset1:11
	ds_read2st64_b32 v[128:129], v64 offset0:12 offset1:13
	ds_read2st64_b32 v[132:133], v64 offset0:14 offset1:15
	ds_read2st64_b32 v[134:135], v64 offset0:16 offset1:17
	ds_read2st64_b32 v[136:137], v64 offset0:18 offset1:19
	ds_read2st64_b32 v[138:139], v64 offset0:20 offset1:21
	ds_read2st64_b32 v[140:141], v64 offset0:22 offset1:23
	ds_read2st64_b32 v[142:143], v64 offset0:24 offset1:25
	ds_read2st64_b32 v[144:145], v64 offset0:26 offset1:27
	ds_read2st64_b32 v[124:125], v64 offset0:28 offset1:29
	ds_read2st64_b32 v[146:147], v64 offset0:30 offset1:31
	ds_read2st64_b32 v[116:117], v64 offset0:32 offset1:33
	ds_read2st64_b32 v[120:121], v64 offset0:34 offset1:35
	ds_read2st64_b32 v[106:107], v64 offset0:36 offset1:37
	ds_read2st64_b32 v[114:115], v64 offset0:38 offset1:39
	ds_read2st64_b32 v[94:95], v64 offset0:40 offset1:41
	ds_read2st64_b32 v[100:101], v64 offset0:42 offset1:43
	ds_read2st64_b32 v[92:93], v64 offset0:44 offset1:45
	ds_read2st64_b32 v[96:97], v64 offset0:46 offset1:47
	ds_read2st64_b32 v[88:89], v64 offset0:56 offset1:57
	ds_read2st64_b32 v[90:91], v64 offset0:58 offset1:59
	ds_read2st64_b32 v[66:67], v64 offset0:60 offset1:61
	ds_read2st64_b32 v[68:69], v64 offset0:62 offset1:63
	ds_read2st64_b32 v[104:105], v64 offset0:48 offset1:49
	ds_read2st64_b32 v[110:111], v64 offset0:50 offset1:51
	ds_read2st64_b32 v[98:99], v64 offset0:52 offset1:53
	ds_read2st64_b32 v[102:103], v64 offset0:54 offset1:55
	s_waitcnt lgkmcnt(14)
	v_pk_mul_f32 v[78:79], v[180:181], v[78:79]
	v_pk_mul_f32 v[80:81], v[180:181], v[80:81]
	v_pk_fma_f32 v[48:49], v[48:49], v[70:71], v[78:79] op_sel_hi:[1,0,1] neg_lo:[0,0,1] neg_hi:[0,0,1]
	v_pk_mul_f32 v[78:79], v[180:181], v[84:85]
	v_pk_fma_f32 v[50:51], v[50:51], v[70:71], v[80:81] op_sel_hi:[1,0,1] neg_lo:[0,0,1] neg_hi:[0,0,1]
	v_pk_fma_f32 v[54:55], v[54:55], v[70:71], v[78:79] op_sel_hi:[1,0,1] neg_lo:[0,0,1] neg_hi:[0,0,1]
	v_pk_mul_f32 v[78:79], v[180:181], v[82:83]
	s_waitcnt lgkmcnt(5)
	v_pk_mul_f32 v[64:65], v[180:181], v[66:67]
	v_pk_fma_f32 v[78:79], v[52:53], v[70:71], v[78:79] op_sel_hi:[1,0,1] neg_lo:[0,0,1] neg_hi:[0,0,1]
	v_pk_mul_f32 v[52:53], v[180:181], v[126:127]
	v_pk_fma_f32 v[64:65], v[12:13], v[70:71], v[64:65] op_sel_hi:[1,0,1] neg_lo:[0,0,1] neg_hi:[0,0,1]
	v_pk_fma_f32 v[52:53], v[58:59], v[70:71], v[52:53] op_sel_hi:[1,0,1] neg_lo:[0,0,1] neg_hi:[0,0,1]
	v_pk_mul_f32 v[58:59], v[180:181], v[86:87]
	s_waitcnt lgkmcnt(4)
	v_pk_mul_f32 v[12:13], v[180:181], v[68:69]
	v_pk_fma_f32 v[80:81], v[56:57], v[70:71], v[58:59] op_sel_hi:[1,0,1] neg_lo:[0,0,1] neg_hi:[0,0,1]
	v_pk_mul_f32 v[56:57], v[180:181], v[132:133]
	v_pk_fma_f32 v[66:67], v[14:15], v[70:71], v[12:13] op_sel_hi:[1,0,1] neg_lo:[0,0,1] neg_hi:[0,0,1]
	v_pk_fma_f32 v[62:63], v[62:63], v[70:71], v[56:57] op_sel_hi:[1,0,1] neg_lo:[0,0,1] neg_hi:[0,0,1]
	v_pk_mul_f32 v[56:57], v[180:181], v[128:129]
	v_lshlrev_b32_e32 v12, 10, v159
	v_pk_fma_f32 v[84:85], v[60:61], v[70:71], v[56:57] op_sel_hi:[1,0,1] neg_lo:[0,0,1] neg_hi:[0,0,1]
	v_pk_mul_f32 v[56:57], v[180:181], v[136:137]
	v_lshl_or_b32 v12, s26, 7, v12
	v_pk_fma_f32 v[56:57], v[34:35], v[70:71], v[56:57] op_sel_hi:[1,0,1] neg_lo:[0,0,1] neg_hi:[0,0,1]
	v_pk_mul_f32 v[34:35], v[180:181], v[134:135]
	v_or_b32_e32 v68, s27, v12
	v_pk_fma_f32 v[60:61], v[32:33], v[70:71], v[34:35] op_sel_hi:[1,0,1] neg_lo:[0,0,1] neg_hi:[0,0,1]
	v_pk_mul_f32 v[32:33], v[180:181], v[140:141]
	v_lshlrev_b32_e32 v130, 1, v68
	v_pk_fma_f32 v[58:59], v[38:39], v[70:71], v[32:33] op_sel_hi:[1,0,1] neg_lo:[0,0,1] neg_hi:[0,0,1]
	v_pk_mul_f32 v[32:33], v[180:181], v[138:139]
	v_lshl_add_u64 v[68:69], s[16:17], 0, v[130:131]
	v_pk_fma_f32 v[82:83], v[36:37], v[70:71], v[32:33] op_sel_hi:[1,0,1] neg_lo:[0,0,1] neg_hi:[0,0,1]
	v_pk_mul_f32 v[32:33], v[180:181], v[144:145]
	v_mov_b32_e32 v159, v131
	v_pk_fma_f32 v[42:43], v[42:43], v[70:71], v[32:33] op_sel_hi:[1,0,1] neg_lo:[0,0,1] neg_hi:[0,0,1]
	v_pk_mul_f32 v[32:33], v[180:181], v[142:143]
	v_pk_mul_f32 v[112:113], v[48:49], v[48:49]
	v_pk_fma_f32 v[86:87], v[40:41], v[70:71], v[32:33] op_sel_hi:[1,0,1] neg_lo:[0,0,1] neg_hi:[0,0,1]
	v_pk_mul_f32 v[32:33], v[180:181], v[146:147]
	global_load_dwordx4 v[12:15], v156, s[40:41]
	v_pk_fma_f32 v[40:41], v[46:47], v[70:71], v[32:33] op_sel_hi:[1,0,1] neg_lo:[0,0,1] neg_hi:[0,0,1]
	v_pk_mul_f32 v[32:33], v[180:181], v[124:125]
	v_lshl_add_u64 v[68:69], v[68:69], 0, v[158:159]
	v_pk_fma_f32 v[44:45], v[44:45], v[70:71], v[32:33] op_sel_hi:[1,0,1] neg_lo:[0,0,1] neg_hi:[0,0,1]
	v_pk_mul_f32 v[32:33], v[180:181], v[120:121]
	v_pk_mul_f32 v[108:109], v[50:51], v[50:51]
	v_pk_fma_f32 v[32:33], v[18:19], v[70:71], v[32:33] op_sel_hi:[1,0,1] neg_lo:[0,0,1] neg_hi:[0,0,1]
	v_pk_mul_f32 v[18:19], v[180:181], v[116:117]
	global_load_dwordx2 v[74:75], v[68:69], off
	v_pk_fma_f32 v[34:35], v[16:17], v[70:71], v[18:19] op_sel_hi:[1,0,1] neg_lo:[0,0,1] neg_hi:[0,0,1]
	v_pk_mul_f32 v[16:17], v[180:181], v[114:115]
	v_pk_mul_f32 v[122:123], v[78:79], v[78:79]
	v_pk_fma_f32 v[36:37], v[22:23], v[70:71], v[16:17] op_sel_hi:[1,0,1] neg_lo:[0,0,1] neg_hi:[0,0,1]
	v_pk_mul_f32 v[16:17], v[180:181], v[106:107]
	v_pk_mul_f32 v[118:119], v[54:55], v[54:55]
	v_pk_fma_f32 v[38:39], v[20:21], v[70:71], v[16:17] op_sel_hi:[1,0,1] neg_lo:[0,0,1] neg_hi:[0,0,1]
	v_pk_mul_f32 v[16:17], v[180:181], v[100:101]
	v_pk_mul_f32 v[148:149], v[80:81], v[80:81]
	v_pk_fma_f32 v[26:27], v[26:27], v[70:71], v[16:17] op_sel_hi:[1,0,1] neg_lo:[0,0,1] neg_hi:[0,0,1]
	v_pk_mul_f32 v[16:17], v[180:181], v[94:95]
	v_pk_mul_f32 v[126:127], v[52:53], v[52:53]
	v_pk_fma_f32 v[24:25], v[24:25], v[70:71], v[16:17] op_sel_hi:[1,0,1] neg_lo:[0,0,1] neg_hi:[0,0,1]
	v_pk_mul_f32 v[16:17], v[180:181], v[96:97]
	v_pk_mul_f32 v[128:129], v[84:85], v[84:85]
	v_pk_fma_f32 v[20:21], v[30:31], v[70:71], v[16:17] op_sel_hi:[1,0,1] neg_lo:[0,0,1] neg_hi:[0,0,1]
	v_pk_mul_f32 v[16:17], v[180:181], v[92:93]
	v_pk_mul_f32 v[132:133], v[62:63], v[62:63]
	v_pk_fma_f32 v[22:23], v[28:29], v[70:71], v[16:17] op_sel_hi:[1,0,1] neg_lo:[0,0,1] neg_hi:[0,0,1]
	s_waitcnt lgkmcnt(2)
	v_pk_mul_f32 v[16:17], v[180:181], v[110:111]
	v_pk_mul_f32 v[134:135], v[60:61], v[60:61]
	v_pk_fma_f32 v[16:17], v[2:3], v[70:71], v[16:17] op_sel_hi:[1,0,1] neg_lo:[0,0,1] neg_hi:[0,0,1]
	v_pk_mul_f32 v[2:3], v[180:181], v[104:105]
	v_pk_mul_f32 v[136:137], v[56:57], v[56:57]
	v_pk_fma_f32 v[18:19], v[0:1], v[70:71], v[2:3] op_sel_hi:[1,0,1] neg_lo:[0,0,1] neg_hi:[0,0,1]
	s_waitcnt lgkmcnt(0)
	v_pk_mul_f32 v[0:1], v[180:181], v[102:103]
	v_pk_mul_f32 v[2:3], v[180:181], v[98:99]
	v_pk_fma_f32 v[0:1], v[6:7], v[70:71], v[0:1] op_sel_hi:[1,0,1] neg_lo:[0,0,1] neg_hi:[0,0,1]
	v_pk_fma_f32 v[4:5], v[4:5], v[70:71], v[2:3] op_sel_hi:[1,0,1] neg_lo:[0,0,1] neg_hi:[0,0,1]
	v_pk_mul_f32 v[2:3], v[180:181], v[90:91]
	v_pk_mul_f32 v[6:7], v[180:181], v[88:89]
	v_pk_fma_f32 v[2:3], v[10:11], v[70:71], v[2:3] op_sel_hi:[1,0,1] neg_lo:[0,0,1] neg_hi:[0,0,1]
	v_pk_fma_f32 v[6:7], v[8:9], v[70:71], v[6:7] op_sel_hi:[1,0,1] neg_lo:[0,0,1] neg_hi:[0,0,1]
	v_add_f32_e32 v70, v112, v113
	v_add_f32_e32 v70, v70, v108
	v_add_f32_e32 v70, v70, v109
	v_add_f32_e32 v70, v70, v122
	v_add_f32_e32 v70, v70, v123
	v_add_f32_e32 v70, v70, v118
	v_add_f32_e32 v70, v70, v119
	v_add_f32_e32 v70, v70, v148
	v_add_f32_e32 v70, v70, v149
	v_add_f32_e32 v70, v70, v126
	v_add_f32_e32 v70, v70, v127
	v_add_f32_e32 v70, v70, v128
	v_add_f32_e32 v70, v70, v129
	v_add_f32_e32 v70, v70, v132
	v_add_f32_e32 v70, v70, v133
	v_add_f32_e32 v70, v70, v134
	v_add_f32_e32 v70, v70, v135
	v_add_f32_e32 v70, v70, v136
	v_pk_mul_f32 v[138:139], v[82:83], v[82:83]
	v_add_f32_e32 v70, v70, v137
	v_add_f32_e32 v70, v70, v138
	v_pk_mul_f32 v[140:141], v[58:59], v[58:59]
	v_add_f32_e32 v70, v70, v139
	v_add_f32_e32 v70, v70, v140
	v_pk_mul_f32 v[142:143], v[86:87], v[86:87]
	v_add_f32_e32 v70, v70, v141
	v_add_f32_e32 v70, v70, v142
	v_pk_mul_f32 v[144:145], v[42:43], v[42:43]
	v_add_f32_e32 v70, v70, v143
	v_add_f32_e32 v70, v70, v144
	v_pk_mul_f32 v[124:125], v[44:45], v[44:45]
	v_add_f32_e32 v70, v70, v145
	v_add_f32_e32 v70, v70, v124
	v_pk_mul_f32 v[46:47], v[40:41], v[40:41]
	v_add_f32_e32 v70, v70, v125
	v_add_f32_e32 v46, v70, v46
	v_pk_mul_f32 v[116:117], v[34:35], v[34:35]
	v_add_f32_e32 v46, v46, v47
	v_add_f32_e32 v46, v46, v116
	v_pk_mul_f32 v[120:121], v[32:33], v[32:33]
	v_add_f32_e32 v46, v46, v117
	v_add_f32_e32 v46, v46, v120
	v_pk_mul_f32 v[106:107], v[38:39], v[38:39]
	v_add_f32_e32 v46, v46, v121
	v_add_f32_e32 v46, v46, v106
	v_pk_mul_f32 v[114:115], v[36:37], v[36:37]
	v_add_f32_e32 v46, v46, v107
	v_add_f32_e32 v46, v46, v114
	v_pk_mul_f32 v[94:95], v[24:25], v[24:25]
	v_add_f32_e32 v46, v46, v115
	v_add_f32_e32 v46, v46, v94
	v_pk_mul_f32 v[100:101], v[26:27], v[26:27]
	v_add_f32_e32 v46, v46, v95
	v_add_f32_e32 v46, v46, v100
	v_pk_mul_f32 v[28:29], v[22:23], v[22:23]
	v_add_f32_e32 v46, v46, v101
	v_add_f32_e32 v28, v46, v28
	v_pk_mul_f32 v[30:31], v[20:21], v[20:21]
	v_add_f32_e32 v28, v28, v29
	v_add_f32_e32 v28, v28, v30
	v_pk_mul_f32 v[96:97], v[18:19], v[18:19]
	v_add_f32_e32 v28, v28, v31
	v_add_f32_e32 v28, v28, v96
	v_pk_mul_f32 v[92:93], v[16:17], v[16:17]
	v_add_f32_e32 v28, v28, v97
	v_add_f32_e32 v28, v28, v92
	v_pk_mul_f32 v[98:99], v[4:5], v[4:5]
	v_add_f32_e32 v28, v28, v93
	v_add_f32_e32 v28, v28, v98
	v_pk_mul_f32 v[102:103], v[0:1], v[0:1]
	v_add_f32_e32 v28, v28, v99
	v_add_f32_e32 v28, v28, v102
	v_pk_mul_f32 v[8:9], v[6:7], v[6:7]
	v_add_f32_e32 v28, v28, v103
	v_add_f32_e32 v8, v28, v8
	v_pk_mul_f32 v[10:11], v[2:3], v[2:3]
	v_add_f32_e32 v8, v8, v9
	v_add_f32_e32 v8, v8, v10
	v_pk_mul_f32 v[72:73], v[64:65], v[64:65]
	v_add_f32_e32 v8, v8, v11
	v_add_f32_e32 v8, v8, v72
	v_pk_mul_f32 v[76:77], v[66:67], v[66:67]
	v_add_f32_e32 v8, v8, v73
	v_add_f32_e32 v8, v8, v76
	v_add_f32_e32 v8, v8, v77
	ds_bpermute_b32 v9, v194, v8
	s_waitcnt vmcnt(0)
	v_lshlrev_b32_e32 v70, 16, v74
	v_and_b32_e32 v71, 0xffff0000, v74
	v_lshlrev_b32_e32 v72, 16, v75
	v_and_b32_e32 v73, 0xffff0000, v75
	s_waitcnt lgkmcnt(0)
	v_add_f32_e32 v8, v8, v9
	v_fmamk_f32 v8, v8, 0x3c000000, v195
	v_mul_f32_e32 v9, 0x4b800000, v8
	v_cmp_gt_f32_e32 vcc, s65, v8
	global_load_dwordx2 v[28:29], v[68:69], off offset:16
	global_load_dwordx2 v[30:31], v[68:69], off offset:32
	global_load_dwordx2 v[46:47], v[68:69], off offset:48
	v_cndmask_b32_e32 v8, v8, v9, vcc
	v_rsq_f32_e32 v10, v8
	v_lshl_add_u64 v[8:9], s[18:19], 0, v[130:131]
	v_lshl_add_u64 v[8:9], v[8:9], 0, v[158:159]
	v_mul_f32_e32 v11, 0x45800000, v10
	v_cndmask_b32_e32 v10, v10, v11, vcc
	v_mul_f32_e32 v10, 0x3f4ccccd, v10
	v_pk_mul_f32 v[48:49], v[48:49], v[10:11] op_sel_hi:[1,0]
	v_pk_mul_f32 v[42:43], v[42:43], v[10:11] op_sel_hi:[1,0]
	v_pk_mul_f32 v[12:13], v[12:13], v[48:49]
	v_pk_mul_f32 v[48:49], v[50:51], v[10:11] op_sel_hi:[1,0]
	v_pk_mul_f32 v[12:13], v[12:13], v[70:71]
	v_pk_mul_f32 v[14:15], v[14:15], v[48:49]
	v_cvt_pk_bf16_f32 v12, v12, v13
	v_pk_mul_f32 v[14:15], v[14:15], v[72:73]
	v_pk_mul_f32 v[50:51], v[78:79], v[10:11] op_sel_hi:[1,0]
	v_cvt_pk_bf16_f32 v13, v14, v15
	global_store_dwordx2 v[8:9], v[12:13], off nt
	global_load_dwordx4 v[12:15], v156, s[40:41] offset:32
	v_pk_mul_f32 v[44:45], v[44:45], v[10:11] op_sel_hi:[1,0]
	v_pk_mul_f32 v[40:41], v[40:41], v[10:11] op_sel_hi:[1,0]
	v_pk_mul_f32 v[34:35], v[34:35], v[10:11] op_sel_hi:[1,0]
	v_pk_mul_f32 v[32:33], v[32:33], v[10:11] op_sel_hi:[1,0]
	v_pk_mul_f32 v[24:25], v[24:25], v[10:11] op_sel_hi:[1,0]
	v_pk_mul_f32 v[26:27], v[26:27], v[10:11] op_sel_hi:[1,0]
	v_pk_mul_f32 v[22:23], v[22:23], v[10:11] op_sel_hi:[1,0]
	v_pk_mul_f32 v[20:21], v[20:21], v[10:11] op_sel_hi:[1,0]
	v_pk_mul_f32 v[18:19], v[18:19], v[10:11] op_sel_hi:[1,0]
	v_pk_mul_f32 v[16:17], v[16:17], v[10:11] op_sel_hi:[1,0]
	v_pk_mul_f32 v[4:5], v[4:5], v[10:11] op_sel_hi:[1,0]
	v_pk_mul_f32 v[0:1], v[0:1], v[10:11] op_sel_hi:[1,0]
	v_pk_mul_f32 v[6:7], v[6:7], v[10:11] op_sel_hi:[1,0]
	v_pk_mul_f32 v[2:3], v[2:3], v[10:11] op_sel_hi:[1,0]
	s_waitcnt vmcnt(4)
	v_lshlrev_b32_e32 v48, 16, v28
	v_and_b32_e32 v49, 0xffff0000, v28
	v_lshlrev_b32_e32 v28, 16, v29
	v_and_b32_e32 v29, 0xffff0000, v29
	s_waitcnt vmcnt(0)
	v_pk_mul_f32 v[12:13], v[12:13], v[50:51]
	s_nop 0
	v_pk_mul_f32 v[12:13], v[12:13], v[48:49]
	v_pk_mul_f32 v[48:49], v[54:55], v[10:11] op_sel_hi:[1,0]
	v_cvt_pk_bf16_f32 v12, v12, v13
	v_pk_mul_f32 v[14:15], v[14:15], v[48:49]
	v_pk_mul_f32 v[48:49], v[80:81], v[10:11] op_sel_hi:[1,0]
	v_pk_mul_f32 v[14:15], v[14:15], v[28:29]
	v_pk_mul_f32 v[50:51], v[52:53], v[10:11] op_sel_hi:[1,0]
	v_cvt_pk_bf16_f32 v13, v14, v15
	global_store_dwordx2 v[8:9], v[12:13], off offset:16 nt
	global_load_dwordx4 v[12:15], v156, s[40:41] offset:64
	v_lshlrev_b32_e32 v28, 16, v30
	v_and_b32_e32 v29, 0xffff0000, v30
	v_lshlrev_b32_e32 v30, 16, v31
	v_and_b32_e32 v31, 0xffff0000, v31
	v_pk_mul_f32 v[52:53], v[60:61], v[10:11] op_sel_hi:[1,0]
	v_pk_mul_f32 v[54:55], v[56:57], v[10:11] op_sel_hi:[1,0]
	s_waitcnt vmcnt(0)
	v_pk_mul_f32 v[12:13], v[48:49], v[12:13]
	v_pk_mul_f32 v[14:15], v[50:51], v[14:15]
	v_pk_mul_f32 v[12:13], v[12:13], v[28:29]
	v_pk_mul_f32 v[14:15], v[14:15], v[30:31]
	v_cvt_pk_bf16_f32 v12, v12, v13
	v_cvt_pk_bf16_f32 v13, v14, v15
	global_store_dwordx2 v[8:9], v[12:13], off offset:32 nt
	global_load_dwordx4 v[12:15], v156, s[40:41] offset:96
	s_nop 0
	global_load_dwordx2 v[28:29], v[68:69], off offset:64
	v_pk_mul_f32 v[48:49], v[84:85], v[10:11] op_sel_hi:[1,0]
	v_pk_mul_f32 v[50:51], v[62:63], v[10:11] op_sel_hi:[1,0]
	v_lshlrev_b32_e32 v30, 16, v46
	v_and_b32_e32 v31, 0xffff0000, v46
	v_lshlrev_b32_e32 v46, 16, v47
	v_and_b32_e32 v47, 0xffff0000, v47
	s_waitcnt vmcnt(1)
	v_pk_mul_f32 v[12:13], v[48:49], v[12:13]
	v_pk_mul_f32 v[14:15], v[50:51], v[14:15]
	v_pk_mul_f32 v[12:13], v[12:13], v[30:31]
	v_pk_mul_f32 v[14:15], v[14:15], v[46:47]
	v_cvt_pk_bf16_f32 v12, v12, v13
	v_cvt_pk_bf16_f32 v13, v14, v15
	global_store_dwordx2 v[8:9], v[12:13], off offset:48 nt
	global_load_dwordx4 v[12:15], v156, s[40:41] offset:128
	s_nop 0
	global_load_dwordx2 v[30:31], v[68:69], off offset:80
	global_load_dwordx2 v[46:47], v[68:69], off offset:96
	global_load_dwordx2 v[48:49], v[68:69], off offset:112
	s_waitcnt vmcnt(5)
	v_lshlrev_b32_e32 v50, 16, v28
	v_and_b32_e32 v51, 0xffff0000, v28
	v_lshlrev_b32_e32 v28, 16, v29
	v_and_b32_e32 v29, 0xffff0000, v29
	s_waitcnt vmcnt(3)
	v_pk_mul_f32 v[12:13], v[52:53], v[12:13]
	v_pk_mul_f32 v[14:15], v[54:55], v[14:15]
	v_pk_mul_f32 v[12:13], v[12:13], v[50:51]
	v_pk_mul_f32 v[14:15], v[14:15], v[28:29]
	v_cvt_pk_bf16_f32 v12, v12, v13
	v_cvt_pk_bf16_f32 v13, v14, v15
	global_store_dwordx2 v[8:9], v[12:13], off offset:64 nt
	global_load_dwordx4 v[12:15], v156, s[40:41] offset:160
	v_pk_mul_f32 v[50:51], v[82:83], v[10:11] op_sel_hi:[1,0]
	v_pk_mul_f32 v[52:53], v[58:59], v[10:11] op_sel_hi:[1,0]
	s_waitcnt vmcnt(4)
	v_lshlrev_b32_e32 v28, 16, v30
	v_and_b32_e32 v29, 0xffff0000, v30
	v_lshlrev_b32_e32 v30, 16, v31
	v_and_b32_e32 v31, 0xffff0000, v31
	s_waitcnt vmcnt(0)
	v_pk_mul_f32 v[12:13], v[50:51], v[12:13]
	v_pk_mul_f32 v[14:15], v[52:53], v[14:15]
	v_pk_mul_f32 v[12:13], v[12:13], v[28:29]
	v_pk_mul_f32 v[14:15], v[14:15], v[30:31]
	v_cvt_pk_bf16_f32 v12, v12, v13
	v_cvt_pk_bf16_f32 v13, v14, v15
	global_store_dwordx2 v[8:9], v[12:13], off offset:80 nt
	global_load_dwordx4 v[12:15], v156, s[40:41] offset:192
	v_lshlrev_b32_e32 v28, 16, v46
	v_and_b32_e32 v29, 0xffff0000, v46
	v_lshlrev_b32_e32 v30, 16, v47
	v_and_b32_e32 v31, 0xffff0000, v47
	v_pk_mul_f32 v[46:47], v[86:87], v[10:11] op_sel_hi:[1,0]
	s_waitcnt vmcnt(0)
	v_pk_mul_f32 v[14:15], v[42:43], v[14:15]
	v_pk_mul_f32 v[12:13], v[46:47], v[12:13]
	v_pk_mul_f32 v[14:15], v[14:15], v[30:31]
	v_pk_mul_f32 v[12:13], v[12:13], v[28:29]
	v_lshlrev_b32_e32 v30, 16, v48
	v_cvt_pk_bf16_f32 v12, v12, v13
	v_cvt_pk_bf16_f32 v13, v14, v15
	global_store_dwordx2 v[8:9], v[12:13], off offset:96 nt
	global_load_dwordx4 v[12:15], v156, s[40:41] offset:224
	s_nop 0
	global_load_dwordx2 v[28:29], v[68:69], off offset:128
	v_and_b32_e32 v31, 0xffff0000, v48
	v_lshlrev_b32_e32 v42, 16, v49
	v_and_b32_e32 v43, 0xffff0000, v49
	s_waitcnt vmcnt(1)
	v_pk_mul_f32 v[12:13], v[44:45], v[12:13]
	v_pk_mul_f32 v[14:15], v[40:41], v[14:15]
	v_pk_mul_f32 v[12:13], v[12:13], v[30:31]
	v_pk_mul_f32 v[14:15], v[14:15], v[42:43]
	v_cvt_pk_bf16_f32 v12, v12, v13
	v_cvt_pk_bf16_f32 v13, v14, v15
	global_store_dwordx2 v[8:9], v[12:13], off offset:112 nt
	global_load_dwordx4 v[12:15], v156, s[40:41] offset:256
	s_nop 0
	global_load_dwordx2 v[30:31], v[68:69], off offset:144
	global_load_dwordx2 v[40:41], v[68:69], off offset:160
	global_load_dwordx2 v[42:43], v[68:69], off offset:176
	s_waitcnt vmcnt(5)
	v_lshlrev_b32_e32 v44, 16, v28
	v_and_b32_e32 v45, 0xffff0000, v28
	v_lshlrev_b32_e32 v28, 16, v29
	v_and_b32_e32 v29, 0xffff0000, v29
	s_waitcnt vmcnt(3)
	v_pk_mul_f32 v[12:13], v[34:35], v[12:13]
	v_pk_mul_f32 v[14:15], v[32:33], v[14:15]
	v_pk_mul_f32 v[12:13], v[12:13], v[44:45]
	v_pk_mul_f32 v[14:15], v[14:15], v[28:29]
	v_cvt_pk_bf16_f32 v12, v12, v13
	v_cvt_pk_bf16_f32 v13, v14, v15
	global_store_dwordx2 v[8:9], v[12:13], off offset:128 nt
	global_load_dwordx4 v[12:15], v156, s[40:41] offset:288
	v_pk_mul_f32 v[32:33], v[38:39], v[10:11] op_sel_hi:[1,0]
	v_pk_mul_f32 v[34:35], v[36:37], v[10:11] op_sel_hi:[1,0]
	s_waitcnt vmcnt(4)
	v_lshlrev_b32_e32 v28, 16, v30
	v_and_b32_e32 v29, 0xffff0000, v30
	v_lshlrev_b32_e32 v30, 16, v31
	v_and_b32_e32 v31, 0xffff0000, v31
	s_waitcnt vmcnt(0)
	v_pk_mul_f32 v[12:13], v[32:33], v[12:13]
	v_pk_mul_f32 v[14:15], v[34:35], v[14:15]
	v_pk_mul_f32 v[12:13], v[12:13], v[28:29]
	v_pk_mul_f32 v[14:15], v[14:15], v[30:31]
	v_cvt_pk_bf16_f32 v12, v12, v13
	v_cvt_pk_bf16_f32 v13, v14, v15
	global_store_dwordx2 v[8:9], v[12:13], off offset:144 nt
	global_load_dwordx4 v[12:15], v156, s[40:41] offset:320
	v_lshlrev_b32_e32 v28, 16, v40
	v_and_b32_e32 v29, 0xffff0000, v40
	v_lshlrev_b32_e32 v30, 16, v41
	v_and_b32_e32 v31, 0xffff0000, v41
	s_waitcnt vmcnt(0)
	v_pk_mul_f32 v[12:13], v[24:25], v[12:13]
	v_pk_mul_f32 v[14:15], v[26:27], v[14:15]
	v_pk_mul_f32 v[12:13], v[12:13], v[28:29]
	v_pk_mul_f32 v[14:15], v[14:15], v[30:31]
	v_cvt_pk_bf16_f32 v12, v12, v13
	v_cvt_pk_bf16_f32 v13, v14, v15
	global_store_dwordx2 v[8:9], v[12:13], off offset:160 nt
	global_load_dwordx4 v[12:15], v156, s[40:41] offset:352
	s_nop 0
	global_load_dwordx2 v[24:25], v[68:69], off offset:192
	v_lshlrev_b32_e32 v26, 16, v42
	v_and_b32_e32 v27, 0xffff0000, v42
	v_lshlrev_b32_e32 v28, 16, v43
	v_and_b32_e32 v29, 0xffff0000, v43
	s_waitcnt vmcnt(1)
	v_pk_mul_f32 v[12:13], v[22:23], v[12:13]
	v_pk_mul_f32 v[14:15], v[20:21], v[14:15]
	v_pk_mul_f32 v[12:13], v[12:13], v[26:27]
	v_pk_mul_f32 v[14:15], v[14:15], v[28:29]
	v_cvt_pk_bf16_f32 v12, v12, v13
	v_cvt_pk_bf16_f32 v13, v14, v15
	global_store_dwordx2 v[8:9], v[12:13], off offset:176 nt
	global_load_dwordx4 v[12:15], v156, s[40:41] offset:384
	s_nop 0
	global_load_dwordx2 v[20:21], v[68:69], off offset:208
	global_load_dwordx2 v[22:23], v[68:69], off offset:224
	global_load_dwordx2 v[26:27], v[68:69], off offset:240
	s_waitcnt vmcnt(5)
	v_lshlrev_b32_e32 v28, 16, v24
	v_and_b32_e32 v29, 0xffff0000, v24
	v_lshlrev_b32_e32 v24, 16, v25
	v_and_b32_e32 v25, 0xffff0000, v25
	s_waitcnt vmcnt(3)
	v_pk_mul_f32 v[12:13], v[18:19], v[12:13]
	v_pk_mul_f32 v[14:15], v[16:17], v[14:15]
	v_pk_mul_f32 v[12:13], v[12:13], v[28:29]
	v_pk_mul_f32 v[14:15], v[14:15], v[24:25]
	v_cvt_pk_bf16_f32 v12, v12, v13
	v_cvt_pk_bf16_f32 v13, v14, v15
	global_store_dwordx2 v[8:9], v[12:13], off offset:192 nt
	global_load_dwordx4 v[12:15], v156, s[40:41] offset:416
	s_waitcnt vmcnt(4)
	v_lshlrev_b32_e32 v16, 16, v20
	v_and_b32_e32 v17, 0xffff0000, v20
	v_lshlrev_b32_e32 v18, 16, v21
	v_and_b32_e32 v19, 0xffff0000, v21
	s_waitcnt vmcnt(0)
	v_pk_mul_f32 v[4:5], v[4:5], v[12:13]
	v_pk_mul_f32 v[0:1], v[0:1], v[14:15]
	v_pk_mul_f32 v[4:5], v[4:5], v[16:17]
	v_pk_mul_f32 v[0:1], v[0:1], v[18:19]
	v_cvt_pk_bf16_f32 v4, v4, v5
	v_cvt_pk_bf16_f32 v5, v0, v1
	global_store_dwordx2 v[8:9], v[4:5], off offset:208 nt
	global_load_dwordx4 v[12:15], v156, s[40:41] offset:448
	v_lshlrev_b32_e32 v0, 16, v22
	v_and_b32_e32 v1, 0xffff0000, v22
	v_lshlrev_b32_e32 v4, 16, v23
	v_and_b32_e32 v5, 0xffff0000, v23
	s_waitcnt vmcnt(0)
	v_pk_mul_f32 v[6:7], v[6:7], v[12:13]
	v_pk_mul_f32 v[2:3], v[2:3], v[14:15]
	v_pk_mul_f32 v[0:1], v[6:7], v[0:1]
	v_pk_mul_f32 v[2:3], v[2:3], v[4:5]
	v_cvt_pk_bf16_f32 v0, v0, v1
	v_cvt_pk_bf16_f32 v1, v2, v3
	global_store_dwordx2 v[8:9], v[0:1], off offset:224 nt
	global_load_dwordx4 v[0:3], v156, s[40:41] offset:480
	v_pk_mul_f32 v[12:13], v[64:65], v[10:11] op_sel_hi:[1,0]
	v_pk_mul_f32 v[10:11], v[66:67], v[10:11] op_sel_hi:[1,0]
	v_lshlrev_b32_e32 v4, 16, v26
	v_and_b32_e32 v5, 0xffff0000, v26
	v_lshlrev_b32_e32 v6, 16, v27
	v_and_b32_e32 v7, 0xffff0000, v27
	s_waitcnt vmcnt(0)
	v_pk_mul_f32 v[0:1], v[12:13], v[0:1]
	v_pk_mul_f32 v[2:3], v[10:11], v[2:3]
	v_pk_mul_f32 v[0:1], v[0:1], v[4:5]
	v_pk_mul_f32 v[2:3], v[2:3], v[6:7]
	v_cvt_pk_bf16_f32 v0, v0, v1
	v_cvt_pk_bf16_f32 v1, v2, v3
	global_store_dwordx2 v[8:9], v[0:1], off offset:240 nt

.LBB0_285:
	v_lshl_add_u64 v[74:75], v[190:191], 0, s[20:21]
	v_lshlrev_b64 v[74:75], 10, v[74:75]
	v_lshl_add_u64 v[74:75], v[74:75], 0, s[22:23]
	v_lshlrev_b64 v[74:75], 1, v[74:75]
	v_lshl_add_u64 v[76:77], v[186:187], 0, v[74:75]
	global_load_dwordx2 v[78:79], v[76:77], off
	global_load_dwordx2 v[80:81], v[76:77], off offset:16
	global_load_dwordx2 v[82:83], v[76:77], off offset:32
	global_load_dwordx2 v[84:85], v[76:77], off offset:48
	global_load_dwordx2 v[86:87], v[76:77], off offset:64
	global_load_dwordx2 v[88:89], v[76:77], off offset:80
	global_load_dwordx2 v[90:91], v[76:77], off offset:96
	v_div_scale_f32 v92, s[26:27], v70, v70, 1.0
	global_load_dwordx2 v[76:77], v[76:77], off offset:112
	v_rcp_f32_e32 v93, v92
	v_div_scale_f32 v94, vcc, 1.0, v70, 1.0
	v_lshl_add_u64 v[74:75], v[188:189], 0, v[74:75]
	v_fma_f32 v95, -v92, v93, 1.0
	v_fmac_f32_e32 v93, v95, v93
	v_mul_f32_e32 v95, v94, v93
	v_fma_f32 v96, -v92, v95, v94
	v_fmac_f32_e32 v95, v96, v93
	v_fma_f32 v92, -v92, v95, v94
	v_div_fmas_f32 v92, v92, v93, v95
	v_div_fixup_f32 v92, v92, v70, 1.0
	v_pk_mul_f32 v[94:95], v[48:49], v[92:93] op_sel_hi:[1,0]
	v_pk_mul_f32 v[96:97], v[50:51], v[92:93] op_sel_hi:[1,0]
	v_pk_mul_f32 v[98:99], v[52:53], v[92:93] op_sel_hi:[1,0]
	v_pk_mul_f32 v[100:101], v[54:55], v[92:93] op_sel_hi:[1,0]
	v_pk_mul_f32 v[102:103], v[56:57], v[92:93] op_sel_hi:[1,0]
	s_waitcnt vmcnt(9)
	v_pk_mul_f32 v[104:105], v[58:59], v[92:93] op_sel_hi:[1,0]
	v_pk_mul_f32 v[106:107], v[60:61], v[92:93] op_sel_hi:[1,0]
	s_waitcnt vmcnt(8)
	v_pk_mul_f32 v[108:109], v[62:63], v[92:93] op_sel_hi:[1,0]
	v_pk_mul_f32 v[110:111], v[32:33], v[92:93] op_sel_hi:[1,0]
	v_pk_mul_f32 v[112:113], v[34:35], v[92:93] op_sel_hi:[1,0]
	v_pk_mul_f32 v[116:117], v[38:39], v[92:93] op_sel_hi:[1,0]
	v_pk_mul_f32 v[114:115], v[36:37], v[92:93] op_sel_hi:[1,0]
	s_waitcnt vmcnt(7)
	v_lshlrev_b32_e32 v118, 16, v78
	v_and_b32_e32 v119, 0xffff0000, v78
	v_lshlrev_b32_e32 v78, 16, v79
	v_and_b32_e32 v79, 0xffff0000, v79
	s_waitcnt vmcnt(6)
	v_lshlrev_b32_e32 v120, 16, v80
	v_and_b32_e32 v121, 0xffff0000, v80
	v_lshlrev_b32_e32 v80, 16, v81
	v_and_b32_e32 v81, 0xffff0000, v81
	s_waitcnt vmcnt(5)
	v_lshlrev_b32_e32 v122, 16, v82
	v_and_b32_e32 v123, 0xffff0000, v82
	v_lshlrev_b32_e32 v82, 16, v83
	v_and_b32_e32 v83, 0xffff0000, v83
	s_waitcnt vmcnt(4)
	v_lshlrev_b32_e32 v124, 16, v84
	v_and_b32_e32 v125, 0xffff0000, v84
	v_lshlrev_b32_e32 v84, 16, v85
	v_and_b32_e32 v85, 0xffff0000, v85
	s_waitcnt vmcnt(3)
	v_lshlrev_b32_e32 v126, 16, v86
	v_and_b32_e32 v127, 0xffff0000, v86
	v_lshlrev_b32_e32 v86, 16, v87
	v_and_b32_e32 v87, 0xffff0000, v87
	v_pk_mul_f32 v[94:95], v[94:95], v[118:119]
	v_pk_mul_f32 v[78:79], v[96:97], v[78:79]
	v_pk_mul_f32 v[96:97], v[98:99], v[120:121]
	v_pk_mul_f32 v[80:81], v[100:101], v[80:81]
	v_pk_mul_f32 v[98:99], v[102:103], v[122:123]
	v_pk_mul_f32 v[82:83], v[104:105], v[82:83]
	v_pk_mul_f32 v[100:101], v[106:107], v[124:125]
	v_pk_mul_f32 v[84:85], v[108:109], v[84:85]
	v_pk_mul_f32 v[102:103], v[110:111], v[126:127]
	v_pk_mul_f32 v[86:87], v[112:113], v[86:87]
	v_cvt_pk_bf16_f32 v94, v94, v95
	v_cvt_pk_bf16_f32 v95, v78, v79
	v_cvt_pk_bf16_f32 v78, v96, v97
	v_cvt_pk_bf16_f32 v79, v80, v81
	v_cvt_pk_bf16_f32 v80, v98, v99
	v_cvt_pk_bf16_f32 v81, v82, v83
	v_cvt_pk_bf16_f32 v82, v100, v101
	v_cvt_pk_bf16_f32 v83, v84, v85
	v_cvt_pk_bf16_f32 v84, v102, v103
	v_cvt_pk_bf16_f32 v85, v86, v87
	global_store_dwordx2 v[74:75], v[94:95], off nt
	global_store_dwordx2 v[74:75], v[78:79], off offset:16 nt
	global_store_dwordx2 v[74:75], v[80:81], off offset:32 nt
	global_store_dwordx2 v[74:75], v[82:83], off offset:48 nt
	global_store_dwordx2 v[74:75], v[84:85], off offset:64 nt
	s_waitcnt vmcnt(7)
	v_lshlrev_b32_e32 v78, 16, v89
	v_and_b32_e32 v79, 0xffff0000, v89
	v_pk_mul_f32 v[78:79], v[116:117], v[78:79]
	s_waitcnt vmcnt(6)
	v_lshlrev_b32_e32 v80, 16, v90
	v_cvt_pk_bf16_f32 v87, v78, v79
	v_pk_mul_f32 v[78:79], v[40:41], v[92:93] op_sel_hi:[1,0]
	v_and_b32_e32 v81, 0xffff0000, v90
	v_pk_mul_f32 v[78:79], v[78:79], v[80:81]
	v_pk_mul_f32 v[80:81], v[42:43], v[92:93] op_sel_hi:[1,0]
	v_lshlrev_b32_e32 v82, 16, v91
	v_and_b32_e32 v83, 0xffff0000, v91
	v_pk_mul_f32 v[80:81], v[80:81], v[82:83]
	v_cvt_pk_bf16_f32 v78, v78, v79
	v_cvt_pk_bf16_f32 v79, v80, v81
	global_store_dwordx2 v[74:75], v[78:79], off offset:96 nt
	v_pk_mul_f32 v[78:79], v[44:45], v[92:93] op_sel_hi:[1,0]
	s_waitcnt vmcnt(6)
	v_lshlrev_b32_e32 v80, 16, v76
	v_and_b32_e32 v81, 0xffff0000, v76
	v_pk_mul_f32 v[78:79], v[78:79], v[80:81]
	v_lshlrev_b32_e32 v132, 16, v88
	v_and_b32_e32 v133, 0xffff0000, v88
	v_cvt_pk_bf16_f32 v76, v78, v79
	v_pk_mul_f32 v[78:79], v[46:47], v[92:93] op_sel_hi:[1,0]
	v_lshlrev_b32_e32 v80, 16, v77
	v_and_b32_e32 v81, 0xffff0000, v77
	v_pk_mul_f32 v[104:105], v[114:115], v[132:133]
	v_pk_mul_f32 v[78:79], v[78:79], v[80:81]
	v_cvt_pk_bf16_f32 v86, v104, v105
	v_cvt_pk_bf16_f32 v77, v78, v79
	global_store_dwordx2 v[74:75], v[86:87], off offset:80 nt
	global_store_dwordx2 v[74:75], v[76:77], off offset:112 nt
	s_cbranch_execnz .LBB0_282

.LBB0_309:
	s_cmpk_gt_u32 s36, 0xff
	s_waitcnt lgkmcnt(0)
	s_barrier
	s_cbranch_scc1 .LBB0_244
	ds_read2st64_b32 v[80:81], v64 offset1:1
	ds_read2st64_b32 v[82:83], v64 offset0:2 offset1:3
	ds_read2st64_b32 v[84:85], v64 offset0:4 offset1:5
	ds_read2st64_b32 v[86:87], v64 offset0:6 offset1:7
	ds_read2st64_b32 v[88:89], v64 offset0:8 offset1:9
	ds_read2st64_b32 v[128:129], v64 offset0:10 offset1:11
	ds_read2st64_b32 v[132:133], v64 offset0:12 offset1:13
	ds_read2st64_b32 v[134:135], v64 offset0:14 offset1:15
	ds_read2st64_b32 v[136:137], v64 offset0:16 offset1:17
	ds_read2st64_b32 v[138:139], v64 offset0:18 offset1:19
	ds_read2st64_b32 v[140:141], v64 offset0:20 offset1:21
	ds_read2st64_b32 v[142:143], v64 offset0:22 offset1:23
	ds_read2st64_b32 v[144:145], v64 offset0:24 offset1:25
	ds_read2st64_b32 v[146:147], v64 offset0:26 offset1:27
	ds_read2st64_b32 v[126:127], v64 offset0:28 offset1:29
	ds_read2st64_b32 v[148:149], v64 offset0:30 offset1:31
	ds_read2st64_b32 v[118:119], v64 offset0:32 offset1:33
	ds_read2st64_b32 v[122:123], v64 offset0:34 offset1:35
	ds_read2st64_b32 v[108:109], v64 offset0:36 offset1:37
	ds_read2st64_b32 v[116:117], v64 offset0:38 offset1:39
	ds_read2st64_b32 v[96:97], v64 offset0:40 offset1:41
	ds_read2st64_b32 v[102:103], v64 offset0:42 offset1:43
	ds_read2st64_b32 v[94:95], v64 offset0:44 offset1:45
	ds_read2st64_b32 v[98:99], v64 offset0:46 offset1:47
	ds_read2st64_b32 v[90:91], v64 offset0:56 offset1:57
	ds_read2st64_b32 v[92:93], v64 offset0:58 offset1:59
	ds_read2st64_b32 v[66:67], v64 offset0:60 offset1:61
	ds_read2st64_b32 v[68:69], v64 offset0:62 offset1:63
	ds_read2st64_b32 v[106:107], v64 offset0:48 offset1:49
	ds_read2st64_b32 v[112:113], v64 offset0:50 offset1:51
	ds_read2st64_b32 v[100:101], v64 offset0:52 offset1:53
	ds_read2st64_b32 v[104:105], v64 offset0:54 offset1:55
	s_waitcnt lgkmcnt(14)
	v_pk_mul_f32 v[80:81], v[180:181], v[80:81]
	v_pk_mul_f32 v[82:83], v[180:181], v[82:83]
	v_pk_fma_f32 v[48:49], v[48:49], v[70:71], v[80:81] op_sel_hi:[1,0,1] neg_lo:[0,0,1] neg_hi:[0,0,1]
	v_pk_mul_f32 v[80:81], v[180:181], v[86:87]
	v_pk_fma_f32 v[50:51], v[50:51], v[70:71], v[82:83] op_sel_hi:[1,0,1] neg_lo:[0,0,1] neg_hi:[0,0,1]
	v_pk_fma_f32 v[54:55], v[54:55], v[70:71], v[80:81] op_sel_hi:[1,0,1] neg_lo:[0,0,1] neg_hi:[0,0,1]
	v_pk_mul_f32 v[80:81], v[180:181], v[84:85]
	s_lshl_b32 s4, s27, 23
	v_pk_fma_f32 v[80:81], v[52:53], v[70:71], v[80:81] op_sel_hi:[1,0,1] neg_lo:[0,0,1] neg_hi:[0,0,1]
	v_pk_mul_f32 v[52:53], v[180:181], v[128:129]
	s_lshl_b32 s5, s26, 7
	v_pk_fma_f32 v[52:53], v[58:59], v[70:71], v[52:53] op_sel_hi:[1,0,1] neg_lo:[0,0,1] neg_hi:[0,0,1]
	v_pk_mul_f32 v[58:59], v[180:181], v[88:89]
	s_add_i32 s5, s5, s4
	v_pk_fma_f32 v[82:83], v[56:57], v[70:71], v[58:59] op_sel_hi:[1,0,1] neg_lo:[0,0,1] neg_hi:[0,0,1]
	v_pk_mul_f32 v[56:57], v[180:181], v[134:135]
	v_lshl_add_u32 v130, v159, 10, s5
	v_pk_fma_f32 v[62:63], v[62:63], v[70:71], v[56:57] op_sel_hi:[1,0,1] neg_lo:[0,0,1] neg_hi:[0,0,1]
	v_pk_mul_f32 v[56:57], v[180:181], v[132:133]
	s_waitcnt lgkmcnt(5)
	v_pk_mul_f32 v[64:65], v[180:181], v[66:67]
	v_pk_fma_f32 v[86:87], v[60:61], v[70:71], v[56:57] op_sel_hi:[1,0,1] neg_lo:[0,0,1] neg_hi:[0,0,1]
	v_pk_mul_f32 v[56:57], v[180:181], v[138:139]
	v_lshlrev_b64 v[72:73], 1, v[130:131]
	v_pk_fma_f32 v[56:57], v[34:35], v[70:71], v[56:57] op_sel_hi:[1,0,1] neg_lo:[0,0,1] neg_hi:[0,0,1]
	v_pk_mul_f32 v[34:35], v[180:181], v[136:137]
	v_pk_fma_f32 v[64:65], v[12:13], v[70:71], v[64:65] op_sel_hi:[1,0,1] neg_lo:[0,0,1] neg_hi:[0,0,1]
	v_pk_fma_f32 v[60:61], v[32:33], v[70:71], v[34:35] op_sel_hi:[1,0,1] neg_lo:[0,0,1] neg_hi:[0,0,1]
	v_pk_mul_f32 v[32:33], v[180:181], v[142:143]
	s_waitcnt lgkmcnt(4)
	v_pk_mul_f32 v[12:13], v[180:181], v[68:69]
	v_pk_fma_f32 v[58:59], v[38:39], v[70:71], v[32:33] op_sel_hi:[1,0,1] neg_lo:[0,0,1] neg_hi:[0,0,1]
	v_pk_mul_f32 v[32:33], v[180:181], v[140:141]
	v_lshl_add_u64 v[68:69], s[16:17], 0, v[72:73]
	v_pk_fma_f32 v[84:85], v[36:37], v[70:71], v[32:33] op_sel_hi:[1,0,1] neg_lo:[0,0,1] neg_hi:[0,0,1]
	v_pk_mul_f32 v[32:33], v[180:181], v[146:147]
	v_mov_b32_e32 v159, v131
	v_pk_fma_f32 v[42:43], v[42:43], v[70:71], v[32:33] op_sel_hi:[1,0,1] neg_lo:[0,0,1] neg_hi:[0,0,1]
	v_pk_mul_f32 v[32:33], v[180:181], v[144:145]
	v_pk_mul_f32 v[114:115], v[48:49], v[48:49]
	v_pk_fma_f32 v[88:89], v[40:41], v[70:71], v[32:33] op_sel_hi:[1,0,1] neg_lo:[0,0,1] neg_hi:[0,0,1]
	v_pk_mul_f32 v[32:33], v[180:181], v[148:149]
	v_pk_fma_f32 v[66:67], v[14:15], v[70:71], v[12:13] op_sel_hi:[1,0,1] neg_lo:[0,0,1] neg_hi:[0,0,1]
	v_pk_fma_f32 v[40:41], v[46:47], v[70:71], v[32:33] op_sel_hi:[1,0,1] neg_lo:[0,0,1] neg_hi:[0,0,1]
	v_pk_mul_f32 v[32:33], v[180:181], v[126:127]
	global_load_dwordx4 v[12:15], v156, s[40:41]
	v_pk_fma_f32 v[44:45], v[44:45], v[70:71], v[32:33] op_sel_hi:[1,0,1] neg_lo:[0,0,1] neg_hi:[0,0,1]
	v_pk_mul_f32 v[32:33], v[180:181], v[122:123]
	v_lshl_add_u64 v[68:69], v[68:69], 0, v[158:159]
	v_pk_fma_f32 v[32:33], v[18:19], v[70:71], v[32:33] op_sel_hi:[1,0,1] neg_lo:[0,0,1] neg_hi:[0,0,1]
	v_pk_mul_f32 v[18:19], v[180:181], v[118:119]
	v_pk_mul_f32 v[110:111], v[50:51], v[50:51]
	v_pk_fma_f32 v[34:35], v[16:17], v[70:71], v[18:19] op_sel_hi:[1,0,1] neg_lo:[0,0,1] neg_hi:[0,0,1]
	v_pk_mul_f32 v[16:17], v[180:181], v[116:117]
	global_load_dwordx2 v[76:77], v[68:69], off
	v_pk_fma_f32 v[36:37], v[22:23], v[70:71], v[16:17] op_sel_hi:[1,0,1] neg_lo:[0,0,1] neg_hi:[0,0,1]
	v_pk_mul_f32 v[16:17], v[180:181], v[108:109]
	v_pk_mul_f32 v[124:125], v[80:81], v[80:81]
	v_pk_fma_f32 v[38:39], v[20:21], v[70:71], v[16:17] op_sel_hi:[1,0,1] neg_lo:[0,0,1] neg_hi:[0,0,1]
	v_pk_mul_f32 v[16:17], v[180:181], v[102:103]
	v_pk_mul_f32 v[120:121], v[54:55], v[54:55]
	v_pk_fma_f32 v[26:27], v[26:27], v[70:71], v[16:17] op_sel_hi:[1,0,1] neg_lo:[0,0,1] neg_hi:[0,0,1]
	v_pk_mul_f32 v[16:17], v[180:181], v[96:97]
	v_pk_mul_f32 v[150:151], v[82:83], v[82:83]
	v_pk_fma_f32 v[24:25], v[24:25], v[70:71], v[16:17] op_sel_hi:[1,0,1] neg_lo:[0,0,1] neg_hi:[0,0,1]
	v_pk_mul_f32 v[16:17], v[180:181], v[98:99]
	v_pk_mul_f32 v[128:129], v[52:53], v[52:53]
	v_pk_fma_f32 v[20:21], v[30:31], v[70:71], v[16:17] op_sel_hi:[1,0,1] neg_lo:[0,0,1] neg_hi:[0,0,1]
	v_pk_mul_f32 v[16:17], v[180:181], v[94:95]
	v_pk_mul_f32 v[132:133], v[86:87], v[86:87]
	v_pk_fma_f32 v[22:23], v[28:29], v[70:71], v[16:17] op_sel_hi:[1,0,1] neg_lo:[0,0,1] neg_hi:[0,0,1]
	s_waitcnt lgkmcnt(2)
	v_pk_mul_f32 v[16:17], v[180:181], v[112:113]
	v_pk_mul_f32 v[134:135], v[62:63], v[62:63]
	v_pk_fma_f32 v[16:17], v[2:3], v[70:71], v[16:17] op_sel_hi:[1,0,1] neg_lo:[0,0,1] neg_hi:[0,0,1]
	v_pk_mul_f32 v[2:3], v[180:181], v[106:107]
	v_pk_mul_f32 v[136:137], v[60:61], v[60:61]
	v_pk_fma_f32 v[18:19], v[0:1], v[70:71], v[2:3] op_sel_hi:[1,0,1] neg_lo:[0,0,1] neg_hi:[0,0,1]
	s_waitcnt lgkmcnt(0)
	v_pk_mul_f32 v[0:1], v[180:181], v[104:105]
	v_pk_mul_f32 v[2:3], v[180:181], v[100:101]
	v_pk_fma_f32 v[0:1], v[6:7], v[70:71], v[0:1] op_sel_hi:[1,0,1] neg_lo:[0,0,1] neg_hi:[0,0,1]
	v_pk_fma_f32 v[4:5], v[4:5], v[70:71], v[2:3] op_sel_hi:[1,0,1] neg_lo:[0,0,1] neg_hi:[0,0,1]
	v_pk_mul_f32 v[2:3], v[180:181], v[92:93]
	v_pk_mul_f32 v[6:7], v[180:181], v[90:91]
	v_pk_fma_f32 v[2:3], v[10:11], v[70:71], v[2:3] op_sel_hi:[1,0,1] neg_lo:[0,0,1] neg_hi:[0,0,1]
	v_pk_fma_f32 v[6:7], v[8:9], v[70:71], v[6:7] op_sel_hi:[1,0,1] neg_lo:[0,0,1] neg_hi:[0,0,1]
	v_add_f32_e32 v70, v114, v115
	v_add_f32_e32 v70, v70, v110
	v_add_f32_e32 v70, v70, v111
	v_add_f32_e32 v70, v70, v124
	v_add_f32_e32 v70, v70, v125
	v_add_f32_e32 v70, v70, v120
	v_add_f32_e32 v70, v70, v121
	v_add_f32_e32 v70, v70, v150
	v_add_f32_e32 v70, v70, v151
	v_add_f32_e32 v70, v70, v128
	v_add_f32_e32 v70, v70, v129
	v_add_f32_e32 v70, v70, v132
	v_add_f32_e32 v70, v70, v133
	v_add_f32_e32 v70, v70, v134
	v_add_f32_e32 v70, v70, v135
	v_add_f32_e32 v70, v70, v136
	v_pk_mul_f32 v[138:139], v[56:57], v[56:57]
	v_add_f32_e32 v70, v70, v137
	v_add_f32_e32 v70, v70, v138
	v_pk_mul_f32 v[140:141], v[84:85], v[84:85]
	v_add_f32_e32 v70, v70, v139
	v_add_f32_e32 v70, v70, v140
	v_pk_mul_f32 v[142:143], v[58:59], v[58:59]
	v_add_f32_e32 v70, v70, v141
	v_add_f32_e32 v70, v70, v142
	v_pk_mul_f32 v[144:145], v[88:89], v[88:89]
	v_add_f32_e32 v70, v70, v143
	v_add_f32_e32 v70, v70, v144
	v_pk_mul_f32 v[146:147], v[42:43], v[42:43]
	v_add_f32_e32 v70, v70, v145
	v_add_f32_e32 v70, v70, v146
	v_pk_mul_f32 v[126:127], v[44:45], v[44:45]
	v_add_f32_e32 v70, v70, v147
	v_add_f32_e32 v70, v70, v126
	v_pk_mul_f32 v[46:47], v[40:41], v[40:41]
	v_add_f32_e32 v70, v70, v127
	v_add_f32_e32 v46, v70, v46
	v_pk_mul_f32 v[118:119], v[34:35], v[34:35]
	v_add_f32_e32 v46, v46, v47
	v_add_f32_e32 v46, v46, v118
	v_pk_mul_f32 v[122:123], v[32:33], v[32:33]
	v_add_f32_e32 v46, v46, v119
	v_add_f32_e32 v46, v46, v122
	v_pk_mul_f32 v[108:109], v[38:39], v[38:39]
	v_add_f32_e32 v46, v46, v123
	v_add_f32_e32 v46, v46, v108
	v_pk_mul_f32 v[116:117], v[36:37], v[36:37]
	v_add_f32_e32 v46, v46, v109
	v_add_f32_e32 v46, v46, v116
	v_pk_mul_f32 v[96:97], v[24:25], v[24:25]
	v_add_f32_e32 v46, v46, v117
	v_add_f32_e32 v46, v46, v96
	v_pk_mul_f32 v[102:103], v[26:27], v[26:27]
	v_add_f32_e32 v46, v46, v97
	v_add_f32_e32 v46, v46, v102
	v_pk_mul_f32 v[28:29], v[22:23], v[22:23]
	v_add_f32_e32 v46, v46, v103
	v_add_f32_e32 v28, v46, v28
	v_pk_mul_f32 v[30:31], v[20:21], v[20:21]
	v_add_f32_e32 v28, v28, v29
	v_add_f32_e32 v28, v28, v30
	v_pk_mul_f32 v[98:99], v[18:19], v[18:19]
	v_add_f32_e32 v28, v28, v31
	v_add_f32_e32 v28, v28, v98
	v_pk_mul_f32 v[94:95], v[16:17], v[16:17]
	v_add_f32_e32 v28, v28, v99
	v_add_f32_e32 v28, v28, v94
	v_pk_mul_f32 v[100:101], v[4:5], v[4:5]
	v_add_f32_e32 v28, v28, v95
	v_add_f32_e32 v28, v28, v100
	v_pk_mul_f32 v[104:105], v[0:1], v[0:1]
	v_add_f32_e32 v28, v28, v101
	v_add_f32_e32 v28, v28, v104
	v_pk_mul_f32 v[8:9], v[6:7], v[6:7]
	v_add_f32_e32 v28, v28, v105
	v_add_f32_e32 v8, v28, v8
	v_pk_mul_f32 v[10:11], v[2:3], v[2:3]
	v_add_f32_e32 v8, v8, v9
	v_add_f32_e32 v8, v8, v10
	v_pk_mul_f32 v[74:75], v[64:65], v[64:65]
	v_add_f32_e32 v8, v8, v11
	v_add_f32_e32 v8, v8, v74
	v_pk_mul_f32 v[78:79], v[66:67], v[66:67]
	v_add_f32_e32 v8, v8, v75
	v_add_f32_e32 v8, v8, v78
	v_add_f32_e32 v8, v8, v79
	ds_bpermute_b32 v9, v194, v8
	s_waitcnt vmcnt(0)
	v_lshlrev_b32_e32 v70, 16, v76
	v_and_b32_e32 v71, 0xffff0000, v76
	v_lshlrev_b32_e32 v74, 16, v77
	v_and_b32_e32 v75, 0xffff0000, v77
	s_waitcnt lgkmcnt(0)
	v_add_f32_e32 v8, v8, v9
	v_fmamk_f32 v8, v8, 0x3c000000, v195
	v_mul_f32_e32 v9, 0x4b800000, v8
	v_cmp_gt_f32_e32 vcc, s65, v8
	global_load_dwordx2 v[28:29], v[68:69], off offset:16
	global_load_dwordx2 v[30:31], v[68:69], off offset:32
	global_load_dwordx2 v[46:47], v[68:69], off offset:48
	v_cndmask_b32_e32 v8, v8, v9, vcc
	v_rsq_f32_e32 v10, v8
	v_lshl_add_u64 v[8:9], s[18:19], 0, v[72:73]
	v_lshl_add_u64 v[8:9], v[8:9], 0, v[158:159]
	v_mul_f32_e32 v11, 0x45800000, v10
	v_cndmask_b32_e32 v10, v10, v11, vcc
	v_mul_f32_e32 v10, 0x3f4ccccd, v10
	v_pk_mul_f32 v[48:49], v[48:49], v[10:11] op_sel_hi:[1,0]
	v_pk_mul_f32 v[42:43], v[42:43], v[10:11] op_sel_hi:[1,0]
	v_pk_mul_f32 v[12:13], v[12:13], v[48:49]
	v_pk_mul_f32 v[48:49], v[50:51], v[10:11] op_sel_hi:[1,0]
	v_pk_mul_f32 v[12:13], v[12:13], v[70:71]
	v_pk_mul_f32 v[14:15], v[14:15], v[48:49]
	v_cvt_pk_bf16_f32 v12, v12, v13
	v_pk_mul_f32 v[14:15], v[14:15], v[74:75]
	v_pk_mul_f32 v[50:51], v[80:81], v[10:11] op_sel_hi:[1,0]
	v_cvt_pk_bf16_f32 v13, v14, v15
	global_store_dwordx2 v[8:9], v[12:13], off nt
	global_load_dwordx4 v[12:15], v156, s[40:41] offset:32
	v_pk_mul_f32 v[44:45], v[44:45], v[10:11] op_sel_hi:[1,0]
	v_pk_mul_f32 v[40:41], v[40:41], v[10:11] op_sel_hi:[1,0]
	v_pk_mul_f32 v[34:35], v[34:35], v[10:11] op_sel_hi:[1,0]
	v_pk_mul_f32 v[32:33], v[32:33], v[10:11] op_sel_hi:[1,0]
	v_pk_mul_f32 v[24:25], v[24:25], v[10:11] op_sel_hi:[1,0]
	v_pk_mul_f32 v[26:27], v[26:27], v[10:11] op_sel_hi:[1,0]
	v_pk_mul_f32 v[22:23], v[22:23], v[10:11] op_sel_hi:[1,0]
	v_pk_mul_f32 v[20:21], v[20:21], v[10:11] op_sel_hi:[1,0]
	v_pk_mul_f32 v[18:19], v[18:19], v[10:11] op_sel_hi:[1,0]
	v_pk_mul_f32 v[16:17], v[16:17], v[10:11] op_sel_hi:[1,0]
	v_pk_mul_f32 v[4:5], v[4:5], v[10:11] op_sel_hi:[1,0]
	v_pk_mul_f32 v[0:1], v[0:1], v[10:11] op_sel_hi:[1,0]
	v_pk_mul_f32 v[6:7], v[6:7], v[10:11] op_sel_hi:[1,0]
	v_pk_mul_f32 v[2:3], v[2:3], v[10:11] op_sel_hi:[1,0]
	s_waitcnt vmcnt(4)
	v_lshlrev_b32_e32 v48, 16, v28
	v_and_b32_e32 v49, 0xffff0000, v28
	v_lshlrev_b32_e32 v28, 16, v29
	v_and_b32_e32 v29, 0xffff0000, v29
	s_waitcnt vmcnt(0)
	v_pk_mul_f32 v[12:13], v[12:13], v[50:51]
	s_nop 0
	v_pk_mul_f32 v[12:13], v[12:13], v[48:49]
	v_pk_mul_f32 v[48:49], v[54:55], v[10:11] op_sel_hi:[1,0]
	v_cvt_pk_bf16_f32 v12, v12, v13
	v_pk_mul_f32 v[14:15], v[14:15], v[48:49]
	v_pk_mul_f32 v[48:49], v[82:83], v[10:11] op_sel_hi:[1,0]
	v_pk_mul_f32 v[14:15], v[14:15], v[28:29]
	v_pk_mul_f32 v[50:51], v[52:53], v[10:11] op_sel_hi:[1,0]
	v_cvt_pk_bf16_f32 v13, v14, v15
	global_store_dwordx2 v[8:9], v[12:13], off offset:16 nt
	global_load_dwordx4 v[12:15], v156, s[40:41] offset:64
	v_lshlrev_b32_e32 v28, 16, v30
	v_and_b32_e32 v29, 0xffff0000, v30
	v_lshlrev_b32_e32 v30, 16, v31
	v_and_b32_e32 v31, 0xffff0000, v31
	v_pk_mul_f32 v[52:53], v[60:61], v[10:11] op_sel_hi:[1,0]
	v_pk_mul_f32 v[54:55], v[56:57], v[10:11] op_sel_hi:[1,0]
	s_waitcnt vmcnt(0)
	v_pk_mul_f32 v[12:13], v[48:49], v[12:13]
	v_pk_mul_f32 v[14:15], v[50:51], v[14:15]
	v_pk_mul_f32 v[12:13], v[12:13], v[28:29]
	v_pk_mul_f32 v[14:15], v[14:15], v[30:31]
	v_cvt_pk_bf16_f32 v12, v12, v13
	v_cvt_pk_bf16_f32 v13, v14, v15
	global_store_dwordx2 v[8:9], v[12:13], off offset:32 nt
	global_load_dwordx4 v[12:15], v156, s[40:41] offset:96
	s_nop 0
	global_load_dwordx2 v[28:29], v[68:69], off offset:64
	v_pk_mul_f32 v[48:49], v[86:87], v[10:11] op_sel_hi:[1,0]
	v_pk_mul_f32 v[50:51], v[62:63], v[10:11] op_sel_hi:[1,0]
	v_lshlrev_b32_e32 v30, 16, v46
	v_and_b32_e32 v31, 0xffff0000, v46
	v_lshlrev_b32_e32 v46, 16, v47
	v_and_b32_e32 v47, 0xffff0000, v47
	s_waitcnt vmcnt(1)
	v_pk_mul_f32 v[12:13], v[48:49], v[12:13]
	v_pk_mul_f32 v[14:15], v[50:51], v[14:15]
	v_pk_mul_f32 v[12:13], v[12:13], v[30:31]
	v_pk_mul_f32 v[14:15], v[14:15], v[46:47]
	v_cvt_pk_bf16_f32 v12, v12, v13
	v_cvt_pk_bf16_f32 v13, v14, v15
	global_store_dwordx2 v[8:9], v[12:13], off offset:48 nt
	global_load_dwordx4 v[12:15], v156, s[40:41] offset:128
	s_nop 0
	global_load_dwordx2 v[30:31], v[68:69], off offset:80
	global_load_dwordx2 v[46:47], v[68:69], off offset:96
	global_load_dwordx2 v[48:49], v[68:69], off offset:112
	s_waitcnt vmcnt(5)
	v_lshlrev_b32_e32 v50, 16, v28
	v_and_b32_e32 v51, 0xffff0000, v28
	v_lshlrev_b32_e32 v28, 16, v29
	v_and_b32_e32 v29, 0xffff0000, v29
	s_waitcnt vmcnt(3)
	v_pk_mul_f32 v[12:13], v[52:53], v[12:13]
	v_pk_mul_f32 v[14:15], v[54:55], v[14:15]
	v_pk_mul_f32 v[12:13], v[12:13], v[50:51]
	v_pk_mul_f32 v[14:15], v[14:15], v[28:29]
	v_cvt_pk_bf16_f32 v12, v12, v13
	v_cvt_pk_bf16_f32 v13, v14, v15
	global_store_dwordx2 v[8:9], v[12:13], off offset:64 nt
	global_load_dwordx4 v[12:15], v156, s[40:41] offset:160
	v_pk_mul_f32 v[50:51], v[84:85], v[10:11] op_sel_hi:[1,0]
	v_pk_mul_f32 v[52:53], v[58:59], v[10:11] op_sel_hi:[1,0]
	s_waitcnt vmcnt(4)
	v_lshlrev_b32_e32 v28, 16, v30
	v_and_b32_e32 v29, 0xffff0000, v30
	v_lshlrev_b32_e32 v30, 16, v31
	v_and_b32_e32 v31, 0xffff0000, v31
	s_waitcnt vmcnt(0)
	v_pk_mul_f32 v[12:13], v[50:51], v[12:13]
	v_pk_mul_f32 v[14:15], v[52:53], v[14:15]
	v_pk_mul_f32 v[12:13], v[12:13], v[28:29]
	v_pk_mul_f32 v[14:15], v[14:15], v[30:31]
	v_cvt_pk_bf16_f32 v12, v12, v13
	v_cvt_pk_bf16_f32 v13, v14, v15
	global_store_dwordx2 v[8:9], v[12:13], off offset:80 nt
	global_load_dwordx4 v[12:15], v156, s[40:41] offset:192
	v_lshlrev_b32_e32 v28, 16, v46
	v_and_b32_e32 v29, 0xffff0000, v46
	v_lshlrev_b32_e32 v30, 16, v47
	v_and_b32_e32 v31, 0xffff0000, v47
	v_pk_mul_f32 v[46:47], v[88:89], v[10:11] op_sel_hi:[1,0]
	s_waitcnt vmcnt(0)
	v_pk_mul_f32 v[14:15], v[42:43], v[14:15]
	v_pk_mul_f32 v[12:13], v[46:47], v[12:13]
	v_pk_mul_f32 v[14:15], v[14:15], v[30:31]
	v_pk_mul_f32 v[12:13], v[12:13], v[28:29]
	v_lshlrev_b32_e32 v30, 16, v48
	v_cvt_pk_bf16_f32 v12, v12, v13
	v_cvt_pk_bf16_f32 v13, v14, v15
	global_store_dwordx2 v[8:9], v[12:13], off offset:96 nt
	global_load_dwordx4 v[12:15], v156, s[40:41] offset:224
	s_nop 0
	global_load_dwordx2 v[28:29], v[68:69], off offset:128
	v_and_b32_e32 v31, 0xffff0000, v48
	v_lshlrev_b32_e32 v42, 16, v49
	v_and_b32_e32 v43, 0xffff0000, v49
	s_waitcnt vmcnt(1)
	v_pk_mul_f32 v[12:13], v[44:45], v[12:13]
	v_pk_mul_f32 v[14:15], v[40:41], v[14:15]
	v_pk_mul_f32 v[12:13], v[12:13], v[30:31]
	v_pk_mul_f32 v[14:15], v[14:15], v[42:43]
	v_cvt_pk_bf16_f32 v12, v12, v13
	v_cvt_pk_bf16_f32 v13, v14, v15
	global_store_dwordx2 v[8:9], v[12:13], off offset:112 nt
	global_load_dwordx4 v[12:15], v156, s[40:41] offset:256
	s_nop 0
	global_load_dwordx2 v[30:31], v[68:69], off offset:144
	global_load_dwordx2 v[40:41], v[68:69], off offset:160
	global_load_dwordx2 v[42:43], v[68:69], off offset:176
	s_waitcnt vmcnt(5)
	v_lshlrev_b32_e32 v44, 16, v28
	v_and_b32_e32 v45, 0xffff0000, v28
	v_lshlrev_b32_e32 v28, 16, v29
	v_and_b32_e32 v29, 0xffff0000, v29
	s_waitcnt vmcnt(3)
	v_pk_mul_f32 v[12:13], v[34:35], v[12:13]
	v_pk_mul_f32 v[14:15], v[32:33], v[14:15]
	v_pk_mul_f32 v[12:13], v[12:13], v[44:45]
	v_pk_mul_f32 v[14:15], v[14:15], v[28:29]
	v_cvt_pk_bf16_f32 v12, v12, v13
	v_cvt_pk_bf16_f32 v13, v14, v15
	global_store_dwordx2 v[8:9], v[12:13], off offset:128 nt
	global_load_dwordx4 v[12:15], v156, s[40:41] offset:288
	v_pk_mul_f32 v[32:33], v[38:39], v[10:11] op_sel_hi:[1,0]
	v_pk_mul_f32 v[34:35], v[36:37], v[10:11] op_sel_hi:[1,0]
	s_waitcnt vmcnt(4)
	v_lshlrev_b32_e32 v28, 16, v30
	v_and_b32_e32 v29, 0xffff0000, v30
	v_lshlrev_b32_e32 v30, 16, v31
	v_and_b32_e32 v31, 0xffff0000, v31
	s_waitcnt vmcnt(0)
	v_pk_mul_f32 v[12:13], v[32:33], v[12:13]
	v_pk_mul_f32 v[14:15], v[34:35], v[14:15]
	v_pk_mul_f32 v[12:13], v[12:13], v[28:29]
	v_pk_mul_f32 v[14:15], v[14:15], v[30:31]
	v_cvt_pk_bf16_f32 v12, v12, v13
	v_cvt_pk_bf16_f32 v13, v14, v15
	global_store_dwordx2 v[8:9], v[12:13], off offset:144 nt
	global_load_dwordx4 v[12:15], v156, s[40:41] offset:320
	v_lshlrev_b32_e32 v28, 16, v40
	v_and_b32_e32 v29, 0xffff0000, v40
	v_lshlrev_b32_e32 v30, 16, v41
	v_and_b32_e32 v31, 0xffff0000, v41
	s_waitcnt vmcnt(0)
	v_pk_mul_f32 v[12:13], v[24:25], v[12:13]
	v_pk_mul_f32 v[14:15], v[26:27], v[14:15]
	v_pk_mul_f32 v[12:13], v[12:13], v[28:29]
	v_pk_mul_f32 v[14:15], v[14:15], v[30:31]
	v_cvt_pk_bf16_f32 v12, v12, v13
	v_cvt_pk_bf16_f32 v13, v14, v15
	global_store_dwordx2 v[8:9], v[12:13], off offset:160 nt
	global_load_dwordx4 v[12:15], v156, s[40:41] offset:352
	s_nop 0
	global_load_dwordx2 v[24:25], v[68:69], off offset:192
	v_lshlrev_b32_e32 v26, 16, v42
	v_and_b32_e32 v27, 0xffff0000, v42
	v_lshlrev_b32_e32 v28, 16, v43
	v_and_b32_e32 v29, 0xffff0000, v43
	s_waitcnt vmcnt(1)
	v_pk_mul_f32 v[12:13], v[22:23], v[12:13]
	v_pk_mul_f32 v[14:15], v[20:21], v[14:15]
	v_pk_mul_f32 v[12:13], v[12:13], v[26:27]
	v_pk_mul_f32 v[14:15], v[14:15], v[28:29]
	v_cvt_pk_bf16_f32 v12, v12, v13
	v_cvt_pk_bf16_f32 v13, v14, v15
	global_store_dwordx2 v[8:9], v[12:13], off offset:176 nt
	global_load_dwordx4 v[12:15], v156, s[40:41] offset:384
	s_nop 0
	global_load_dwordx2 v[20:21], v[68:69], off offset:208
	global_load_dwordx2 v[22:23], v[68:69], off offset:224
	global_load_dwordx2 v[26:27], v[68:69], off offset:240
	s_waitcnt vmcnt(5)
	v_lshlrev_b32_e32 v28, 16, v24
	v_and_b32_e32 v29, 0xffff0000, v24
	v_lshlrev_b32_e32 v24, 16, v25
	v_and_b32_e32 v25, 0xffff0000, v25
	s_waitcnt vmcnt(3)
	v_pk_mul_f32 v[12:13], v[18:19], v[12:13]
	v_pk_mul_f32 v[14:15], v[16:17], v[14:15]
	v_pk_mul_f32 v[12:13], v[12:13], v[28:29]
	v_pk_mul_f32 v[14:15], v[14:15], v[24:25]
	v_cvt_pk_bf16_f32 v12, v12, v13
	v_cvt_pk_bf16_f32 v13, v14, v15
	global_store_dwordx2 v[8:9], v[12:13], off offset:192 nt
	global_load_dwordx4 v[12:15], v156, s[40:41] offset:416
	s_waitcnt vmcnt(4)
	v_lshlrev_b32_e32 v16, 16, v20
	v_and_b32_e32 v17, 0xffff0000, v20
	v_lshlrev_b32_e32 v18, 16, v21
	v_and_b32_e32 v19, 0xffff0000, v21
	s_waitcnt vmcnt(0)
	v_pk_mul_f32 v[4:5], v[4:5], v[12:13]
	v_pk_mul_f32 v[0:1], v[0:1], v[14:15]
	v_pk_mul_f32 v[4:5], v[4:5], v[16:17]
	v_pk_mul_f32 v[0:1], v[0:1], v[18:19]
	v_cvt_pk_bf16_f32 v4, v4, v5
	v_cvt_pk_bf16_f32 v5, v0, v1
	global_store_dwordx2 v[8:9], v[4:5], off offset:208 nt
	global_load_dwordx4 v[12:15], v156, s[40:41] offset:448
	v_lshlrev_b32_e32 v0, 16, v22
	v_and_b32_e32 v1, 0xffff0000, v22
	v_lshlrev_b32_e32 v4, 16, v23
	v_and_b32_e32 v5, 0xffff0000, v23
	s_waitcnt vmcnt(0)
	v_pk_mul_f32 v[6:7], v[6:7], v[12:13]
	v_pk_mul_f32 v[2:3], v[2:3], v[14:15]
	v_pk_mul_f32 v[0:1], v[6:7], v[0:1]
	v_pk_mul_f32 v[2:3], v[2:3], v[4:5]
	v_cvt_pk_bf16_f32 v0, v0, v1
	v_cvt_pk_bf16_f32 v1, v2, v3
	global_store_dwordx2 v[8:9], v[0:1], off offset:224 nt
	global_load_dwordx4 v[0:3], v156, s[40:41] offset:480
	v_pk_mul_f32 v[12:13], v[64:65], v[10:11] op_sel_hi:[1,0]
	v_pk_mul_f32 v[10:11], v[66:67], v[10:11] op_sel_hi:[1,0]
	v_lshlrev_b32_e32 v4, 16, v26
	v_and_b32_e32 v5, 0xffff0000, v26
	v_lshlrev_b32_e32 v6, 16, v27
	v_and_b32_e32 v7, 0xffff0000, v27
	s_waitcnt vmcnt(0)
	v_pk_mul_f32 v[0:1], v[12:13], v[0:1]
	v_pk_mul_f32 v[2:3], v[10:11], v[2:3]
	v_pk_mul_f32 v[0:1], v[0:1], v[4:5]
	v_pk_mul_f32 v[2:3], v[2:3], v[6:7]
	v_cvt_pk_bf16_f32 v0, v0, v1
	v_cvt_pk_bf16_f32 v1, v2, v3
	global_store_dwordx2 v[8:9], v[0:1], off offset:240 nt
	s_branch .LBB0_244
